# RWKV first segment: state group precomputes silu gate into LDS in S3, output-group epilogue LDS reads batched two tiles ahead; RWKV params loaded at mixer entry
# speedup vs baseline: 1.0788x; 1.0006x over previous
.LBB0_366:
	s_mov_b32 s0, -1
	s_add_i32 s61, s1, 0xffffff50
	v_mbcnt_lo_u32_b32 v0, s0, 0
	v_mbcnt_hi_u32_b32 v0, s0, v0
	v_or_b32_e32 v190, s43, v0
	s_mov_b32 s53, s93
	v_readfirstlane_b32 s0, v190
	s_ashr_i32 s60, s0, 6
	s_lshl_b32 s0, s61, 8
	s_and_b32 s52, s0, 0x7ffff800
	v_writelane_b32 v253, s54, 56
	s_and_b32 s96, s1, 1
	s_and_b32 s97, s60, 3
	s_lshl_b64 s[2:3], s[52:53], 10
	v_writelane_b32 v253, s55, 57
	s_add_u32 s54, s46, s2
	s_addc_u32 s55, s47, s3
	s_lshl_b32 s0, s61, 5
	v_and_b32_e32 v161, 63, v0
	s_and_b32 s2, s0, 0xc0
	v_mov_b32_e32 v0, v161
	s_cmp_lt_i32 s60, 4
	v_writelane_b32 v252, s46, 22
	s_cselect_b64 s[28:29], -1, 0
	s_cmp_gt_i32 s60, 3
	v_and_b32_e32 v1, 15, v0
	v_ashrrev_i32_e32 v0, 2, v0
	v_writelane_b32 v252, s47, 21
	s_mov_b32 s3, s93
	s_cselect_b64 s[30:31], -1, 0
	s_lshl_b32 s0, s97, 4
	v_and_b32_e32 v0, -4, v0
	s_mul_i32 s37, s52, 0x2200
	v_writelane_b32 v252, s2, 27
	v_readlane_b32 s98, v253, 19
	v_readlane_b32 s99, v253, 20
	v_readlane_b32 s100, v252, 17
	v_readlane_b32 s101, v252, 18
	s_lshl_b64 s[98:99], s[98:99], 2
	s_add_u32 s98, s100, s98
	s_addc_u32 s99, s101, s99
	s_lshl_b32 s100, s2, 2
	s_add_u32 s98, s98, s100
	s_addc_u32 s99, s99, 0
	s_or_b32 s100, s2, s84
	v_lshlrev_b32_e32 v192, 2, v161
	global_load_dword v196, v192, s[98:99] offset:1024
	global_load_dword v198, v192, s[98:99]
	global_load_dword v200, v192, s[98:99] offset:2048
	v_add_u32_e32 v192, s100, v161
	v_lshlrev_b32_e32 v192, 2, v192
	global_load_dword v197, v192, s[78:79]
	global_load_dword v201, v192, s[80:81]
	global_load_dword v192, v192, s[76:77]
	v_add_u32_e32 v0, s0, v0
	s_mul_hi_u32 s36, s52, 0x2200
	v_writelane_b32 v252, s3, 28
	v_cmp_eq_u32_e64 s[2:3], v0, v1
	s_add_u32 s38, s44, s37
	v_or_b32_e32 v2, 1, v0
	v_writelane_b32 v252, s2, 1
	s_addc_u32 s39, s45, s36
	s_lshl_b64 s[36:37], s[52:53], 9
	v_writelane_b32 v252, s3, 2
	v_cmp_eq_u32_e64 s[2:3], v2, v1
	s_add_u32 s36, s72, s36
	v_or_b32_e32 v4, 2, v0
	v_writelane_b32 v252, s2, 3
	v_or_b32_e32 v5, 3, v0
	v_or_b32_e32 v6, 16, v1
	s_addc_u32 s37, s73, s37
	v_writelane_b32 v252, s3, 4
	v_cmp_eq_u32_e64 s[6:7], v4, v1
	v_cmp_eq_u32_e64 s[8:9], v5, v1
	v_cmp_eq_u32_e64 s[10:11], v0, v6
	v_cmp_eq_u32_e64 s[12:13], v2, v6
	v_cmp_eq_u32_e64 s[14:15], v4, v6
	v_cmp_eq_u32_e64 s[16:17], v5, v6
	v_or_b32_e32 v6, 32, v1
	v_or_b32_e32 v1, 48, v1
	s_add_u32 s56, s36, 0xde00000
	v_cmp_eq_u32_e64 s[18:19], v0, v6
	v_cmp_eq_u32_e64 s[20:21], v2, v6
	v_cmp_eq_u32_e64 s[22:23], v4, v6
	v_cmp_eq_u32_e64 s[24:25], v5, v6
	v_cmp_eq_u32_e64 s[26:27], v0, v1
	v_cmp_eq_u32_e64 s[2:3], v2, v1
	v_cmp_eq_u32_e64 s[4:5], v4, v1
	v_cmp_eq_u32_e64 s[34:35], v5, v1
	v_writelane_b32 v252, s38, 29
	s_addc_u32 s57, s37, 0
	s_and_b64 vcc, exec, s[28:29]
	v_writelane_b32 v253, s43, 58
	v_writelane_b32 v252, s39, 30
	s_cbranch_vccnz .LBB0_420
	v_mov_b32_e32 v0, v190
	s_lshl_b32 s46, s96, 10
	v_add_u32_e32 v32, 0xffffff00, v0
	s_add_i32 s58, s46, -1
	v_ashrrev_i32_e32 v2, 4, v32
	v_lshlrev_b32_e32 v1, 2, v0
	v_add_u32_e32 v2, s58, v2
	s_movk_i32 s36, 0x510
	v_and_b32_e32 v1, 60, v1
	v_cmp_gt_i32_e32 vcc, s36, v0
	v_cmp_lt_i32_e64 s[36:37], -1, v2
	s_and_b64 s[38:39], vcc, s[36:37]
	v_mov_b32_e32 v4, 0
	v_lshlrev_b32_e32 v24, 2, v1
	v_mov_b32_e32 v8, 0
	v_mov_b32_e32 v9, 0
	v_mov_b32_e32 v10, 0
	v_mov_b32_e32 v11, 0
	s_and_saveexec_b64 s[36:37], s[38:39]
	s_cbranch_execz .LBB0_369
	v_lshlrev_b64 v[6:7], 10, v[2:3]
	v_readlane_b32 s38, v252, 27
	v_lshl_add_u64 v[6:7], s[54:55], 0, v[6:7]
	s_lshl_b32 s92, s38, 2
	v_lshl_add_u64 v[6:7], v[6:7], 0, s[92:93]
	v_mov_b32_e32 v25, v3
	v_lshl_add_u64 v[6:7], v[6:7], 0, v[24:25]
	global_load_dwordx4 v[8:11], v[6:7], off
	v_readlane_b32 s39, v252, 28

.LBB0_420:
	s_lshr_b32 s38, s61, 1
	s_cmp_eq_u32 s96, 0
	s_cselect_b64 s[40:41], -1, 0
	s_and_b64 s[36:37], s[40:41], exec
	s_cselect_b32 s59, 16, 32
	s_lshl_b32 s66, s96, 4
	v_mov_b32_e32 v171, 0
	s_cmp_ge_u32 s66, s59
	v_mov_b32_e32 v170, v171
	v_mov_b32_e32 v175, v171
	v_mov_b32_e32 v174, v171
	v_mov_b32_e32 v169, v171
	v_mov_b32_e32 v168, v171
	v_mov_b32_e32 v173, v171
	v_mov_b32_e32 v172, v171
	v_mov_b32_e32 v151, v171
	v_mov_b32_e32 v150, v171
	v_mov_b32_e32 v153, v171
	v_mov_b32_e32 v152, v171
	v_mov_b32_e32 v155, v171
	v_mov_b32_e32 v154, v171
	v_mov_b32_e32 v149, v171
	v_mov_b32_e32 v148, v171
	s_waitcnt lgkmcnt(0)
	s_barrier
	s_cbranch_scc1 .LBB0_573
	v_writelane_b32 v252, s40, 31
	v_cndmask_b32_e64 v54, 0, 1.0, s[6:7]
	s_waitcnt vmcnt(0)
	v_cndmask_b32_e64 v18, 0, 1.0, s[4:5]
	v_writelane_b32 v252, s41, 32
	v_cndmask_b32_e64 v19, 0, 1.0, s[34:35]
	v_readlane_b32 s6, v252, 27
	s_lshl_b32 s4, s6, 2
	s_add_u32 s34, s54, s4
	v_readlane_b32 s36, v252, 1
	s_addc_u32 s35, s55, 0
	s_lshl_b32 s92, s6, 1
	v_readlane_b32 s37, v252, 2
	v_cndmask_b32_e64 v17, 0, 1.0, s[2:3]
	s_add_u32 s2, s56, s92
	v_cndmask_b32_e64 v52, 0, 1.0, s[36:37]
	v_readlane_b32 s36, v252, 3
	s_addc_u32 s3, s57, 0
	v_readlane_b32 s37, v252, 4
	v_readlane_b32 s7, v252, 28
	v_writelane_b32 v252, s2, 33
	v_cndmask_b32_e64 v55, 0, 1.0, s[8:9]
	v_readlane_b32 s5, v253, 48
	v_writelane_b32 v252, s3, 34
	s_mul_i32 s2, s38, 0x41000
	s_add_i32 s2, s2, 0x3800000
	s_cmp_lt_u32 s61, 62
	s_cselect_b32 s8, s2, 0x2e81000
	s_cmp_lg_u32 s96, 0
	s_cselect_b64 s[40:41], -1, 0
	s_cmp_eq_u32 s96, 0
	v_writelane_b32 v252, s38, 35
	s_cselect_b64 s[2:3], -1, 0
	v_writelane_b32 v252, s2, 1
	v_cndmask_b32_e64 v56, 0, 1.0, s[10:11]
	v_cndmask_b32_e64 v57, 0, 1.0, s[12:13]
	v_writelane_b32 v252, s3, 2
	s_lshl_b64 s[2:3], s[52:53], 11
	s_add_u32 s10, s5, s2
	v_readlane_b32 s2, v253, 50
	s_addc_u32 s11, s2, s3
	v_writelane_b32 v252, s10, 36
	v_readlane_b32 s2, v253, 19
	v_cndmask_b32_e64 v58, 0, 1.0, s[14:15]
	v_writelane_b32 v252, s11, 37
	v_readlane_b32 s3, v253, 20
	v_readlane_b32 s12, v252, 15
	s_lshl_b64 s[2:3], s[2:3], 2
	v_readlane_b32 s14, v252, 17
	v_readlane_b32 s15, v252, 18
	s_add_u32 s2, s14, s2
	s_addc_u32 s3, s15, s3
	s_add_u32 s46, s2, s4
	s_addc_u32 s47, s3, 0
	s_mul_i32 s2, s97, 0x1800
	s_add_i32 s53, 0, 0x12000
	s_add_i32 s2, s53, s2
	v_readlane_b32 s13, v252, 16
	v_writelane_b32 v252, s2, 3
	s_lshl_b32 s2, s0, 2
	s_lshl_b32 s4, s0, 1
	s_add_i32 s9, s2, 0
	v_cndmask_b32_e64 v16, 0, 1.0, s[26:27]
	s_or_b32 s27, s6, s84
	s_add_i32 s55, s4, 0
	s_add_i32 s2, s9, 0x18500
	s_cmp_lg_u32 s97, 0
	s_cselect_b64 s[48:49], -1, 0
	s_cmp_eq_u32 s97, 3
	v_writelane_b32 v252, s2, 38
	s_cselect_b64 s[2:3], -1, 0
	s_add_i32 s5, s55, 0x20a00
	s_add_i32 s60, s60, -4
	s_cmp_eq_u32 s60, 0
	v_writelane_b32 v252, s5, 39
	s_cselect_b64 s[6:7], -1, 0
	v_writelane_b32 v252, s6, 40
	s_lshl_b32 s5, s60, 10
	s_add_i32 s4, s53, s4
	v_writelane_b32 v252, s7, 41
	v_writelane_b32 v252, s5, 42
	s_lshl_b32 s5, s97, 10
	s_add_i32 s5, s5, 0
	s_add_i32 s5, s5, 0x16800
	v_writelane_b32 v252, s5, 25
	s_lshl_b32 s5, s97, 9
	s_add_i32 s5, s5, 0
	s_add_i32 s5, s5, 0x17800
	s_cmp_gt_u32 s97, 1
	v_cndmask_b32_e64 v53, 0, 1.0, s[36:37]
	v_writelane_b32 v252, s5, 43
	s_cselect_b64 s[36:37], -1, 0
	s_cmp_eq_u32 s97, 1
	v_writelane_b32 v252, s4, 44
	s_cselect_b64 s[4:5], -1, 0
	s_cmp_eq_u32 s97, 2
	s_cselect_b64 s[6:7], -1, 0
	s_add_i32 s9, s9, 0x18400
	v_writelane_b32 v252, s9, 45
	s_lshl_b32 s9, s97, 12
	s_add_i32 s11, 0, 0x18600
	s_add_i32 s9, s11, s9
	v_writelane_b32 v252, s9, 5
	s_mul_i32 s9, s97, 0x900
	v_writelane_b32 v252, s9, 46
	s_or_b32 s9, s0, 1
	s_lshl_b32 s10, s9, 8
	s_add_i32 s10, s11, s10
	v_writelane_b32 v253, s10, 61
	s_mul_i32 s10, s9, 0x90
	v_writelane_b32 v252, s10, 47
	s_lshl_b32 s10, s0, 8
	s_add_i32 s61, s11, s10
	s_add_i32 s10, s61, 0x200
	v_writelane_b32 v253, s10, 63
	s_add_i32 s10, s61, 0x300
	v_writelane_b32 v252, s11, 48
	v_writelane_b32 v253, s10, 59
	s_add_i32 s10, s61, 0x400
	v_writelane_b32 v252, s10, 19
	s_add_i32 s10, s61, 0x500
	v_writelane_b32 v252, s10, 24
	s_add_i32 s10, s61, 0x600
	v_writelane_b32 v252, s10, 23
	s_mul_i32 s10, s97, 0x480
	s_nor_b64 s[44:45], s[40:41], s[28:29]
	s_add_i32 s43, s61, 0x700
	s_add_i32 s52, s61, 0x800
	s_add_i32 s54, s61, 0x900
	s_add_i32 s67, s61, 0xa00
	s_add_i32 s56, s61, 0xb00
	s_add_i32 s57, s61, 0xc00
	s_add_i32 s58, s61, 0xd00
	s_add_i32 s60, s61, 0xe00
	s_addk_i32 s61, 0xf00
	v_writelane_b32 v252, s10, 49
	s_mulk_i32 s9, 0x48
	v_writelane_b32 v252, s9, 50
	s_cmp_lg_u32 s97, 2
	s_mul_i32 s9, s96, 0x41000
	s_cselect_b64 s[82:83], -1, 0
	s_add_u32 s8, s9, s8
	s_addc_u32 s9, 0, 0
	s_add_u32 s8, s72, s8
	s_addc_u32 s9, s73, s9
	s_add_u32 s38, s8, 0xbdbf000
	s_addc_u32 s39, s9, 0
	s_lshl_b32 s8, s96, 10
	v_mov_b32_e32 v148, 0
	v_cndmask_b32_e64 v11, 0, 1.0, s[16:17]
	v_cndmask_b32_e64 v12, 0, 1.0, s[18:19]
	v_cndmask_b32_e64 v13, 0, 1.0, s[20:21]
	v_cndmask_b32_e64 v14, 0, 1.0, s[22:23]
	v_cndmask_b32_e64 v15, 0, 1.0, s[24:25]
	s_or_b32 s42, s8, 63
	v_mov_b32_e32 v149, v148
	v_mov_b32_e32 v154, v148
	v_mov_b32_e32 v155, v148
	v_mov_b32_e32 v152, v148
	v_mov_b32_e32 v153, v148
	v_mov_b32_e32 v150, v148
	v_mov_b32_e32 v151, v148
	v_mov_b32_e32 v172, v148
	v_mov_b32_e32 v173, v148
	v_mov_b32_e32 v168, v148
	v_mov_b32_e32 v169, v148
	v_mov_b32_e32 v174, v148
	v_mov_b32_e32 v175, v148
	v_mov_b32_e32 v170, v148
	v_mov_b32_e32 v171, v148
	s_mov_b32 s96, 0x2aaaaaab
	s_movk_i32 s97, 0xffe8
	v_writelane_b32 v252, s27, 51
	v_add_u32_e32 v250, 0xffffff00, v190
	v_lshrrev_b32_e32 v224, 4, v250
	v_lshlrev_b32_e32 v224, 10, v224
	v_and_b32_e32 v251, 15, v250
	v_lshl_or_b32 v224, v251, 4, v224
	v_add_u32_e32 v225, 0x4000, v224
	v_add_u32_e32 v226, 0x8000, v224
	v_add_u32_e32 v227, 0xc000, v224
	v_min_u32_e32 v251, 15, v250
	v_lshlrev_b32_e32 v228, 4, v251
	v_add_u32_e32 v228, 0x10000, v228
	v_lshrrev_b32_e32 v229, 3, v250
	v_lshlrev_b32_e32 v229, 9, v229
	v_and_b32_e32 v251, 7, v250
	v_lshl_or_b32 v229, v251, 4, v229
	v_add_u32_e32 v242, 0x4000, v229
	s_mov_b32 s98, 0xaaaaaaab
	v_mov_b32_e32 v251, v250
	v_min_u32_e32 v251, 0x617, v251
	v_mul_hi_u32 v254, v251, s98
	v_lshrrev_b32_e32 v254, 4, v254
	v_mul_u32_u24_e32 v255, 24, v254
	v_sub_u32_e32 v255, v251, v255
	v_lshrrev_b32_e32 v255, 3, v255
	v_mul_u32_u24_e32 v243, 0x2200, v254
	v_lshl_add_u32 v243, v255, 9, v243
	v_and_b32_e32 v255, 7, v251
	v_lshl_add_u32 v243, v255, 4, v243
	v_add_u32_e32 v251, 0x100, v250
	v_min_u32_e32 v251, 0x617, v251
	v_mul_hi_u32 v254, v251, s98
	v_lshrrev_b32_e32 v254, 4, v254
	v_mul_u32_u24_e32 v255, 24, v254
	v_sub_u32_e32 v255, v251, v255
	v_lshrrev_b32_e32 v255, 3, v255
	v_mul_u32_u24_e32 v244, 0x2200, v254
	v_lshl_add_u32 v244, v255, 9, v244
	v_and_b32_e32 v255, 7, v251
	v_lshl_add_u32 v244, v255, 4, v244
	v_add_u32_e32 v251, 0x200, v250
	v_min_u32_e32 v251, 0x617, v251
	v_mul_hi_u32 v254, v251, s98
	v_lshrrev_b32_e32 v254, 4, v254
	v_mul_u32_u24_e32 v255, 24, v254
	v_sub_u32_e32 v255, v251, v255
	v_lshrrev_b32_e32 v255, 3, v255
	v_mul_u32_u24_e32 v245, 0x2200, v254
	v_lshl_add_u32 v245, v255, 9, v245
	v_and_b32_e32 v255, 7, v251
	v_lshl_add_u32 v245, v255, 4, v245
	v_add_u32_e32 v251, 0x300, v250
	v_min_u32_e32 v251, 0x617, v251
	v_mul_hi_u32 v254, v251, s98
	v_lshrrev_b32_e32 v254, 4, v254
	v_mul_u32_u24_e32 v255, 24, v254
	v_sub_u32_e32 v255, v251, v255
	v_lshrrev_b32_e32 v255, 3, v255
	v_mul_u32_u24_e32 v246, 0x2200, v254
	v_lshl_add_u32 v246, v255, 9, v246
	v_and_b32_e32 v255, 7, v251
	v_lshl_add_u32 v246, v255, 4, v246
	v_add_u32_e32 v251, 0x400, v250
	v_min_u32_e32 v251, 0x617, v251
	v_mul_hi_u32 v254, v251, s98
	v_lshrrev_b32_e32 v254, 4, v254
	v_mul_u32_u24_e32 v255, 24, v254
	v_sub_u32_e32 v255, v251, v255
	v_lshrrev_b32_e32 v255, 3, v255
	v_mul_u32_u24_e32 v247, 0x2200, v254
	v_lshl_add_u32 v247, v255, 9, v247
	v_and_b32_e32 v255, 7, v251
	v_lshl_add_u32 v247, v255, 4, v247
	v_add_u32_e32 v251, 0x500, v250
	v_min_u32_e32 v251, 0x617, v251
	v_mul_hi_u32 v254, v251, s98
	v_lshrrev_b32_e32 v254, 4, v254
	v_mul_u32_u24_e32 v255, 24, v254
	v_sub_u32_e32 v255, v251, v255
	v_lshrrev_b32_e32 v255, 3, v255
	v_mul_u32_u24_e32 v248, 0x2200, v254
	v_lshl_add_u32 v248, v255, 9, v248
	v_and_b32_e32 v255, 7, v251
	v_lshl_add_u32 v248, v255, 4, v248
	v_add_u32_e32 v251, 0x600, v250
	v_min_u32_e32 v251, 0x617, v251
	v_mul_hi_u32 v254, v251, s98
	v_lshrrev_b32_e32 v254, 4, v254
	v_mul_u32_u24_e32 v255, 24, v254
	v_sub_u32_e32 v255, v251, v255
	v_lshrrev_b32_e32 v255, 3, v255
	v_mul_u32_u24_e32 v249, 0x2200, v254
	v_lshl_add_u32 v249, v255, 9, v249
	v_and_b32_e32 v255, 7, v251
	v_lshl_add_u32 v249, v255, 4, v249

.LBB0_426:
	v_mov_b64_e32 v[20:21], v[52:53]
	v_mov_b64_e32 v[26:27], v[58:59]
	v_mov_b64_e32 v[34:35], v[66:67]
	v_mov_b64_e32 v[22:23], v[54:55]
	v_mov_b64_e32 v[24:25], v[56:57]
	v_mov_b64_e32 v[28:29], v[60:61]
	v_mov_b64_e32 v[30:31], v[62:63]
	v_mov_b64_e32 v[32:33], v[64:65]
	v_mov_b32_e32 v27, v11
	v_mov_b64_e32 v[50:51], v[34:35]
	v_mov_b64_e32 v[46:47], v[30:31]
	v_mov_b64_e32 v[44:45], v[28:29]
	v_mov_b64_e32 v[48:49], v[32:33]
	v_mov_b64_e32 v[42:43], v[26:27]
	v_mov_b64_e32 v[40:41], v[24:25]
	v_mov_b64_e32 v[38:39], v[22:23]
	v_mov_b64_e32 v[36:37], v[20:21]
	v_mov_b32_e32 v44, v12
	v_mov_b32_e32 v45, v13
	v_mov_b32_e32 v46, v14
	v_mov_b32_e32 v47, v15
	v_mov_b64_e32 v[74:75], v[50:51]
	v_mov_b64_e32 v[72:73], v[48:49]
	v_cndmask_b32_e64 v8, 0, 1, s[48:49]
	v_mov_b64_e32 v[70:71], v[46:47]
	v_mov_b64_e32 v[68:69], v[44:45]
	v_mov_b64_e32 v[66:67], v[42:43]
	v_mov_b64_e32 v[64:65], v[40:41]
	v_mov_b64_e32 v[62:63], v[38:39]
	v_mov_b64_e32 v[60:61], v[36:37]
	v_mov_b32_e32 v72, v16
	v_mov_b32_e32 v73, v17
	v_mov_b32_e32 v74, v18
	v_mov_b32_e32 v75, v19
	s_and_b64 vcc, exec, s[12:13]
	v_cmp_ne_u32_e64 s[8:9], 1, v8
	s_cbranch_vccz .LBB0_434
	s_cmp_lg_u64 s[40:41], 0
	s_cbranch_scc1 .Lrz_skip1
	v_and_b32_e32 v20, 15, v161
	s_add_i32 s98, s0, s42
	v_add_u32_e32 v20, s98, v20
	v_subrev_u32_e32 v20, 63, v20
	v_mul_lo_u32 v20, v20, s64
	v_lshrrev_b32_e32 v21, 4, v161
	v_lshl_add_u32 v20, v21, 3, v20
	v_add_u32_e32 v20, s92, v20
	v_add_u32_e32 v20, 0x1e00, v20
	v_readlane_b32 s98, v252, 29
	v_readlane_b32 s99, v252, 30
	s_nop 4
	global_load_dwordx2 v[184:185], v20, s[98:99]
	global_load_dwordx2 v[186:187], v20, s[98:99] offset:32
	global_load_dwordx2 v[188:189], v20, s[98:99] offset:64
	global_load_dwordx2 v[224:225], v20, s[98:99] offset:96
.Lrz_skip1:
	v_lshl_add_u64 v[6:7], v[6:7], 2, s[76:77]
	v_mov_b32_e32 v50, v192
	s_add_i32 s10, 0, 0x1ca00
	v_mov_b32_e32 v6, s53
	ds_read_u16 v51, v59 offset:6272
	v_add_u32_e32 v8, s10, v77
	s_movk_i32 s10, 0x180
	v_mad_u32_u24 v6, v76, s10, v6
	v_lshlrev_b32_e32 v7, 7, v76
	v_add3_u32 v6, v6, v77, v78
	v_add3_u32 v136, v8, v78, v7
	ds_read_b64_tr_b16 v[8:9], v6 offset:128
	ds_read_b64_tr_b16 v[30:31], v6 offset:1664
	ds_read_b64_tr_b16 v[48:49], v6 offset:3200
	ds_read_b64_tr_b16 v[78:79], v6 offset:4736
	ds_read_b64_tr_b16 v[82:83], v136
	ds_read_b64_tr_b16 v[76:77], v136 offset:512
	ds_read_b64_tr_b16 v[28:29], v136 offset:1024
	ds_read_b64_tr_b16 v[6:7], v136 offset:1536
	s_waitcnt lgkmcnt(4)
	v_lshlrev_b32_e32 v84, 16, v79
	v_and_b32_e32 v85, 0xffff0000, v79
	v_and_b32_e32 v79, 0xffff0000, v78
	v_lshlrev_b32_e32 v78, 16, v78
	v_and_b32_e32 v87, 0xffff0000, v49
	v_lshlrev_b32_e32 v86, 16, v49
	v_and_b32_e32 v49, 0xffff0000, v48
	v_lshlrev_b32_e32 v48, 16, v48
	v_and_b32_e32 v89, 0xffff0000, v31
	v_lshlrev_b32_e32 v88, 16, v31
	v_and_b32_e32 v31, 0xffff0000, v30
	v_lshlrev_b32_e32 v30, 16, v30
	v_and_b32_e32 v91, 0xffff0000, v9
	v_lshlrev_b32_e32 v90, 16, v9
	v_and_b32_e32 v9, 0xffff0000, v8
	v_lshlrev_b32_e32 v8, 16, v8
	v_lshlrev_b32_e32 v81, 16, v51
	v_mov_b32_e32 v80, v85
	v_pk_mov_b32 v[92:93], v[78:79], v[84:85] op_sel:[1,0]
	v_pk_mov_b32 v[94:95], v[86:87], v[78:79] op_sel:[1,0]
	v_pk_mov_b32 v[96:97], v[48:49], v[86:87] op_sel:[1,0]
	v_pk_mov_b32 v[102:103], v[88:89], v[48:49] op_sel:[1,0]
	v_pk_mov_b32 v[104:105], v[30:31], v[88:89] op_sel:[1,0]
	v_pk_mov_b32 v[106:107], v[90:91], v[30:31] op_sel:[1,0]
	v_pk_mov_b32 v[124:125], v[8:9], v[90:91] op_sel:[1,0]
	v_pk_add_f32 v[84:85], v[84:85], v[80:81] neg_lo:[0,1] neg_hi:[0,1]
	v_pk_add_f32 v[78:79], v[78:79], v[92:93] neg_lo:[0,1] neg_hi:[0,1]
	v_pk_add_f32 v[98:99], v[86:87], v[94:95] neg_lo:[0,1] neg_hi:[0,1]
	v_pk_add_f32 v[48:49], v[48:49], v[96:97] neg_lo:[0,1] neg_hi:[0,1]
	v_pk_add_f32 v[88:89], v[88:89], v[102:103] neg_lo:[0,1] neg_hi:[0,1]
	v_pk_add_f32 v[30:31], v[30:31], v[104:105] neg_lo:[0,1] neg_hi:[0,1]
	v_pk_add_f32 v[90:91], v[90:91], v[106:107] neg_lo:[0,1] neg_hi:[0,1]
	v_pk_add_f32 v[8:9], v[8:9], v[124:125] neg_lo:[0,1] neg_hi:[0,1]
	v_pk_fma_f32 v[84:85], v[4:5], v[84:85], v[80:81] op_sel_hi:[0,1,1]
	v_pk_fma_f32 v[86:87], v[4:5], v[78:79], v[92:93] op_sel_hi:[0,1,1]
	v_pk_fma_f32 v[98:99], v[4:5], v[98:99], v[94:95] op_sel_hi:[0,1,1]
	v_pk_fma_f32 v[100:101], v[4:5], v[48:49], v[96:97] op_sel_hi:[0,1,1]
	v_pk_fma_f32 v[102:103], v[4:5], v[88:89], v[102:103] op_sel_hi:[0,1,1]
	v_pk_fma_f32 v[104:105], v[4:5], v[30:31], v[104:105] op_sel_hi:[0,1,1]
	v_pk_fma_f32 v[106:107], v[4:5], v[90:91], v[106:107] op_sel_hi:[0,1,1]
	v_pk_fma_f32 v[124:125], v[4:5], v[8:9], v[124:125] op_sel_hi:[0,1,1]
	v_cmp_eq_u32_e32 vcc, 0, v10
	v_readlane_b32 s12, v252, 5
	v_pk_mul_f32 v[8:9], v[50:51], v[84:85] op_sel_hi:[0,1]
	v_pk_mul_f32 v[30:31], v[50:51], v[86:87] op_sel_hi:[0,1]
	v_pk_mul_f32 v[48:49], v[50:51], v[98:99] op_sel_hi:[0,1]
	v_pk_mul_f32 v[88:89], v[50:51], v[100:101] op_sel_hi:[0,1]
	v_pk_mul_f32 v[92:93], v[50:51], v[102:103] op_sel_hi:[0,1]
	v_pk_mul_f32 v[94:95], v[50:51], v[104:105] op_sel_hi:[0,1]
	v_pk_mul_f32 v[80:81], v[50:51], v[106:107] op_sel_hi:[0,1]
	v_pk_mul_f32 v[96:97], v[50:51], v[124:125] op_sel_hi:[0,1]
	v_pk_mul_f32 v[50:51], v[8:9], v[8:9]
	v_pk_mul_f32 v[78:79], v[30:31], v[30:31]
	v_pk_mul_f32 v[90:91], v[48:49], v[48:49]
	v_pk_mul_f32 v[126:127], v[88:89], v[88:89]
	v_pk_mul_f32 v[128:129], v[92:93], v[92:93]
	v_pk_mul_f32 v[130:131], v[94:95], v[94:95]
	v_pk_mul_f32 v[132:133], v[80:81], v[80:81]
	v_pk_mul_f32 v[134:135], v[96:97], v[96:97]
	s_nop 0
	s_nop 1
	v_permlane32_swap_b32 v134, v126
	s_nop 1
	v_permlane32_swap_b32 v135, v127
	s_nop 1
	v_permlane32_swap_b32 v132, v90
	s_nop 1
	v_permlane32_swap_b32 v133, v91
	s_nop 1
	v_permlane32_swap_b32 v130, v78
	s_nop 1
	v_permlane32_swap_b32 v131, v79
	s_nop 1
	v_permlane32_swap_b32 v128, v50
	s_nop 0
	v_add_f32_e32 v4, v134, v126
	v_add_f32_e32 v59, v135, v127
	v_add_f32_e32 v90, v132, v90
	v_add_f32_e32 v78, v130, v78
	v_add_f32_e32 v79, v131, v79
	v_add_f32_e32 v50, v128, v50
	s_nop 1
	v_permlane32_swap_b32 v129, v51
	v_add_f32_e32 v91, v133, v91
	v_add_f32_e32 v51, v129, v51
	s_nop 1
	v_permlane16_swap_b32 v4, v78
	s_nop 1
	v_permlane16_swap_b32 v59, v79
	s_nop 1
	v_permlane16_swap_b32 v90, v50
	s_nop 1
	v_permlane16_swap_b32 v91, v51
	s_nop 0
	v_add_f32_e32 v4, v4, v78
	v_add_f32_e32 v50, v90, v50
	v_add_f32_e32 v59, v59, v79
	v_add_f32_e32 v51, v91, v51
	v_cndmask_b32_e32 v10, v4, v50, vcc
	v_cndmask_b32_e32 v4, v50, v4, vcc
	v_cndmask_b32_e32 v50, v51, v59, vcc
	s_nop 0
	v_add_f32_dpp v4, v10, v4 quad_perm:[2,3,0,1] row_mask:0xf bank_mask:0xf bound_ctrl:1
	v_cndmask_b32_e32 v10, v59, v51, vcc
	v_cmp_eq_u32_e32 vcc, 0, v5
	v_lshl_add_u32 v59, v0, 2, s12
	v_add_f32_dpp v10, v10, v50 quad_perm:[2,3,0,1] row_mask:0xf bank_mask:0xf bound_ctrl:1
	v_cndmask_b32_e32 v5, v4, v10, vcc
	v_cndmask_b32_e32 v4, v10, v4, vcc
	s_and_b64 vcc, exec, s[8:9]
	s_nop 0
	v_add_f32_dpp v4, v5, v4 quad_perm:[1,0,3,2] row_mask:0xf bank_mask:0xf bound_ctrl:1
	s_nop 1
	v_add_f32_dpp v4, v4, v4 row_ror:4 row_mask:0xf bank_mask:0xf bound_ctrl:1
	s_nop 1
	v_add_f32_dpp v126, v4, v4 row_ror:8 row_mask:0xf bank_mask:0xf bound_ctrl:1
	ds_read_b64_tr_b16 v[4:5], v136 offset:1536
	ds_read_b64_tr_b16 v[78:79], v136
	ds_read_b64_tr_b16 v[90:91], v136 offset:512
	ds_read_b64_tr_b16 v[50:51], v136 offset:1024
	ds_read_b32 v10, v59 offset:256
	v_readlane_b32 s10, v126, 0
	v_readlane_b32 s11, v126, 1
	v_readlane_b32 s24, v126, 2
	v_readlane_b32 s25, v126, 3
	v_readlane_b32 s22, v126, 16
	v_readlane_b32 s23, v126, 17
	v_readlane_b32 s20, v126, 18
	v_readlane_b32 s21, v126, 19
	v_readlane_b32 s18, v126, 32
	v_readlane_b32 s19, v126, 33
	v_readlane_b32 s16, v126, 34
	v_readlane_b32 s17, v126, 35
	v_readlane_b32 s14, v126, 48
	v_readlane_b32 s15, v126, 49
	v_readlane_b32 s12, v126, 50
	v_readlane_b32 s13, v126, 51
	s_cbranch_vccnz .LBB0_429
	ds_read_b32 v59, v59
	s_waitcnt lgkmcnt(0)
	v_mul_f32_e32 v59, 0x3fb8aa3b, v59
	s_branch .LBB0_430

.LBB0_455:
	v_mov_b64_e32 v[90:91], v[66:67]
	v_mov_b64_e32 v[88:89], v[64:65]
	v_mov_b64_e32 v[86:87], v[62:63]
	v_mov_b64_e32 v[84:85], v[60:61]
	v_mov_b64_e32 v[78:79], v[54:55]
	v_mov_b64_e32 v[76:77], v[52:53]
	s_andn2_b64 vcc, exec, s[28:29]
	v_mov_b64_e32 v[82:83], v[58:59]
	v_mov_b64_e32 v[80:81], v[56:57]
	s_cbranch_vccnz .LBB0_485
	v_mov_b32_e32 v1, v161
	v_readlane_b32 s12, v252, 44
	v_and_b32_e32 v59, 15, v1
	v_and_b32_e32 v9, -16, v1
	s_waitcnt vmcnt(0)
	s_cmp_lg_u64 s[40:41], 0
	s_cbranch_scc1 .Lrz_skip2
	s_lshl_b32 s98, s0, 8
	s_add_i32 s98, s98, 0x20a00
	v_lshl_add_u32 v36, v161, 4, s98
	v_lshlrev_b32_e32 v32, 16, v184
	v_and_b32_e32 v33, 0xffff0000, v184
	v_mul_f32_e32 v34, 0xbfb8aa3b, v32
	v_mul_f32_e32 v35, 0xbfb8aa3b, v33
	v_exp_f32_e32 v34, v34
	v_exp_f32_e32 v35, v35
	s_nop 0
	v_add_f32_e32 v34, 1.0, v34
	v_add_f32_e32 v35, 1.0, v35
	v_rcp_f32_e32 v34, v34
	v_rcp_f32_e32 v35, v35
	s_nop 0
	v_pk_mul_f32 v[76:77], v[34:35], v[32:33]
	v_lshlrev_b32_e32 v32, 16, v185
	v_and_b32_e32 v33, 0xffff0000, v185
	v_mul_f32_e32 v34, 0xbfb8aa3b, v32
	v_mul_f32_e32 v35, 0xbfb8aa3b, v33
	v_exp_f32_e32 v34, v34
	v_exp_f32_e32 v35, v35
	s_nop 0
	v_add_f32_e32 v34, 1.0, v34
	v_add_f32_e32 v35, 1.0, v35
	v_rcp_f32_e32 v34, v34
	v_rcp_f32_e32 v35, v35
	s_nop 0
	v_pk_mul_f32 v[78:79], v[34:35], v[32:33]
	ds_write_b128 v36, v[76:79]
	v_lshlrev_b32_e32 v32, 16, v186
	v_and_b32_e32 v33, 0xffff0000, v186
	v_mul_f32_e32 v34, 0xbfb8aa3b, v32
	v_mul_f32_e32 v35, 0xbfb8aa3b, v33
	v_exp_f32_e32 v34, v34
	v_exp_f32_e32 v35, v35
	s_nop 0
	v_add_f32_e32 v34, 1.0, v34
	v_add_f32_e32 v35, 1.0, v35
	v_rcp_f32_e32 v34, v34
	v_rcp_f32_e32 v35, v35
	s_nop 0
	v_pk_mul_f32 v[86:87], v[34:35], v[32:33]
	v_lshlrev_b32_e32 v32, 16, v187
	v_and_b32_e32 v33, 0xffff0000, v187
	v_mul_f32_e32 v34, 0xbfb8aa3b, v32
	v_mul_f32_e32 v35, 0xbfb8aa3b, v33
	v_exp_f32_e32 v34, v34
	v_exp_f32_e32 v35, v35
	s_nop 0
	v_add_f32_e32 v34, 1.0, v34
	v_add_f32_e32 v35, 1.0, v35
	v_rcp_f32_e32 v34, v34
	v_rcp_f32_e32 v35, v35
	s_nop 0
	v_pk_mul_f32 v[88:89], v[34:35], v[32:33]
	ds_write_b128 v36, v[86:89] offset:1024
	v_lshlrev_b32_e32 v32, 16, v188
	v_and_b32_e32 v33, 0xffff0000, v188
	v_mul_f32_e32 v34, 0xbfb8aa3b, v32
	v_mul_f32_e32 v35, 0xbfb8aa3b, v33
	v_exp_f32_e32 v34, v34
	v_exp_f32_e32 v35, v35
	s_nop 0
	v_add_f32_e32 v34, 1.0, v34
	v_add_f32_e32 v35, 1.0, v35
	v_rcp_f32_e32 v34, v34
	v_rcp_f32_e32 v35, v35
	s_nop 0
	v_pk_mul_f32 v[76:77], v[34:35], v[32:33]
	v_lshlrev_b32_e32 v32, 16, v189
	v_and_b32_e32 v33, 0xffff0000, v189
	v_mul_f32_e32 v34, 0xbfb8aa3b, v32
	v_mul_f32_e32 v35, 0xbfb8aa3b, v33
	v_exp_f32_e32 v34, v34
	v_exp_f32_e32 v35, v35
	s_nop 0
	v_add_f32_e32 v34, 1.0, v34
	v_add_f32_e32 v35, 1.0, v35
	v_rcp_f32_e32 v34, v34
	v_rcp_f32_e32 v35, v35
	s_nop 0
	v_pk_mul_f32 v[78:79], v[34:35], v[32:33]
	ds_write_b128 v36, v[76:79] offset:2048
	v_lshlrev_b32_e32 v32, 16, v224
	v_and_b32_e32 v33, 0xffff0000, v224
	v_mul_f32_e32 v34, 0xbfb8aa3b, v32
	v_mul_f32_e32 v35, 0xbfb8aa3b, v33
	v_exp_f32_e32 v34, v34
	v_exp_f32_e32 v35, v35
	s_nop 0
	v_add_f32_e32 v34, 1.0, v34
	v_add_f32_e32 v35, 1.0, v35
	v_rcp_f32_e32 v34, v34
	v_rcp_f32_e32 v35, v35
	s_nop 0
	v_pk_mul_f32 v[86:87], v[34:35], v[32:33]
	v_lshlrev_b32_e32 v32, 16, v225
	v_and_b32_e32 v33, 0xffff0000, v225
	v_mul_f32_e32 v34, 0xbfb8aa3b, v32
	v_mul_f32_e32 v35, 0xbfb8aa3b, v33
	v_exp_f32_e32 v34, v34
	v_exp_f32_e32 v35, v35
	s_nop 0
	v_add_f32_e32 v34, 1.0, v34
	v_add_f32_e32 v35, 1.0, v35
	v_rcp_f32_e32 v34, v34
	v_rcp_f32_e32 v35, v35
	s_nop 0
	v_pk_mul_f32 v[88:89], v[34:35], v[32:33]
	ds_write_b128 v36, v[86:89] offset:3072
.Lrz_skip2:
	v_or_b32_e32 v2, s0, v59
	v_add_u32_e32 v0, 0, v9
	v_mad_u32_u24 v2, v2, s89, v0
	ds_read_b128 v[4:7], v2
	v_mul_u32_u24_e32 v8, 0x48, v59
	v_lshl_add_u32 v80, v8, 1, v0
	ds_read_b128 v[48:51], v80 offset:18432
	ds_read_b128 v[28:31], v2 offset:64
	ds_read_b128 v[92:95], v80 offset:18496
	v_ashrrev_i32_e32 v2, 2, v1
	s_waitcnt lgkmcnt(2)
	v_mfma_f32_16x16x32_bf16 v[48:51], v[4:7], v[48:51], 0
	ds_read_b128 v[96:99], v80 offset:27648
	ds_read_b128 v[100:103], v80 offset:27712
	v_and_b32_e32 v1, -4, v2
	v_sub_u32_e32 v10, v59, v1
	s_waitcnt lgkmcnt(2)
	v_mfma_f32_16x16x32_bf16 v[92:95], v[28:31], v[92:95], v[48:51]
	v_lshl_add_u32 v81, v1, 1, s12
	v_cmp_gt_i32_e64 s[12:13], 0, v10
	s_or_b64 s[14:15], s[48:49], s[12:13]
	s_waitcnt lgkmcnt(1)
	v_mfma_f32_16x16x32_bf16 v[96:99], v[96:99], v[4:7], 0
	s_and_b64 vcc, exec, s[8:9]
	s_nop 1
	v_cndmask_b32_e64 v82, 0, -v92, s[14:15]
	v_cmp_gt_i32_e64 s[14:15], 1, v10
	s_or_b64 s[16:17], s[48:49], s[14:15]
	v_cndmask_b32_e64 v83, 0, -v93, s[16:17]
	v_cmp_gt_i32_e64 s[16:17], 2, v10
	s_or_b64 s[18:19], s[48:49], s[16:17]
	s_waitcnt lgkmcnt(0)
	v_mfma_f32_16x16x32_bf16 v[48:51], v[100:103], v[28:31], v[96:99]
	v_cndmask_b32_e64 v92, 0, -v94, s[18:19]
	v_cmp_gt_i32_e64 s[18:19], 3, v10
	s_or_b64 s[20:21], s[48:49], s[18:19]
	v_cndmask_b32_e64 v10, 0, -v95, s[20:21]
	v_cvt_pk_bf16_f32 v82, v82, v83
	v_cvt_pk_bf16_f32 v83, v92, v10
	v_mad_u32_u24 v10, v59, s89, v81
	ds_write_b64 v10, v[82:83]
	s_cbranch_vccnz .LBB0_458
	s_mov_b64 s[20:21], 0
	s_branch .LBB0_459

.LBB0_548:
	v_readlane_b32 s14, v252, 1
	v_readlane_b32 s15, v252, 2
	v_lshlrev_b32_e32 v40, 2, v2
	s_mov_b64 s[12:13], -1
	s_and_b64 vcc, exec, s[14:15]
	s_cbranch_vccz .LBB0_550
	v_add_f32_e32 v2, v20, v21
	v_add_f32_e32 v8, v22, v23
	v_add_f32_e32 v2, v2, v8
	v_add_f32_e32 v8, v24, v25
	v_add_f32_e32 v9, v26, v27
	v_add_f32_e32 v2, 0, v2
	v_add_f32_e32 v8, v8, v9
	v_add_f32_e32 v2, v2, v8
	v_add_f32_e32 v8, v32, v33
	v_add_f32_e32 v9, v34, v35
	v_add_f32_e32 v8, v8, v9
	v_add_f32_e32 v2, v2, v8
	v_mov_b32_e32 v8, v37
	v_mov_b32_e32 v9, v38
	v_mov_b32_e32 v10, v36
	v_mov_b32_e32 v11, v39
	v_pk_add_f32 v[8:9], v[8:9], v[10:11]
	s_add_i32 s12, s0, s42
	v_add_f32_e32 v8, v8, v9
	v_and_b32_e32 v9, 64, v234
	v_add_f32_e32 v2, v2, v8
	v_xor_b32_e32 v8, 16, v234
	v_add_u32_e32 v9, 64, v9
	v_cmp_lt_i32_e32 vcc, v8, v9
	v_lshlrev_b32_e32 v56, 16, v188
	v_and_b32_e32 v57, 0xffff0000, v188
	v_cndmask_b32_e32 v8, v234, v8, vcc
	v_lshlrev_b32_e32 v16, 2, v8
	ds_bpermute_b32 v8, v16, v2
	v_readlane_b32 s14, v252, 27
	v_readlane_b32 s15, v252, 28
	s_waitcnt lgkmcnt(0)
	v_add_f32_e32 v2, v2, v8
	v_xor_b32_e32 v8, 32, v234
	v_cmp_lt_i32_e32 vcc, v8, v9
	v_add_u32_e32 v44, s14, v40
	v_ashrrev_i32_e32 v45, 31, v44
	v_cndmask_b32_e32 v8, v234, v8, vcc
	v_lshlrev_b32_e32 v17, 2, v8
	ds_bpermute_b32 v8, v17, v2
	s_waitcnt lgkmcnt(0)
	v_add_f32_e32 v18, v2, v8
	v_fmamk_f32 v149, v18, 0xbc800000, v21
	v_fmamk_f32 v148, v18, 0xbc800000, v20
	v_fmamk_f32 v155, v18, 0xbc800000, v23
	v_fmamk_f32 v154, v18, 0xbc800000, v22
	v_pk_mul_f32 v[8:9], v[154:155], v[154:155]
	v_pk_mul_f32 v[10:11], v[148:149], v[148:149]
	v_fmamk_f32 v153, v18, 0xbc800000, v25
	v_pk_mov_b32 v[12:13], v[10:11], v[8:9] op_sel:[1,0]
	v_mov_b32_e32 v11, v9
	v_fmamk_f32 v152, v18, 0xbc800000, v24
	v_fmamk_f32 v151, v18, 0xbc800000, v27
	v_fmamk_f32 v150, v18, 0xbc800000, v26
	v_pk_add_f32 v[8:9], v[12:13], v[10:11]
	v_pk_mul_f32 v[10:11], v[150:151], v[150:151]
	v_pk_mul_f32 v[12:13], v[152:153], v[152:153]
	v_fmamk_f32 v172, v18, 0xbc800000, v32
	v_pk_mov_b32 v[14:15], v[12:13], v[10:11] op_sel:[1,0]
	v_mov_b32_e32 v13, v11
	v_fmamk_f32 v168, v18, 0xbc800000, v34
	v_fmamk_f32 v173, v18, 0xbc800000, v33
	v_mul_f32_e32 v2, v172, v172
	v_pk_add_f32 v[10:11], v[14:15], v[12:13]
	v_fmamk_f32 v169, v18, 0xbc800000, v35
	v_pk_fma_f32 v[12:13], v[172:173], v[172:173], v[2:3] op_sel_hi:[1,1,0]
	v_mul_f32_e32 v2, v168, v168
	v_pk_add_f32 v[8:9], v[8:9], v[8:9] op_sel_hi:[0,1]
	v_pk_add_f32 v[10:11], v[10:11], v[10:11] op_sel_hi:[0,1]
	v_pk_fma_f32 v[14:15], v[168:169], v[168:169], v[2:3] op_sel_hi:[1,1,0]
	v_fmamk_f32 v171, v18, 0xbc800000, v39
	v_fmamk_f32 v170, v18, 0xbc800000, v38
	v_fmamk_f32 v175, v18, 0xbc800000, v37
	v_fmamk_f32 v174, v18, 0xbc800000, v36
	v_mul_f32_e32 v12, v174, v174
	v_mul_f32_e32 v14, v175, v175
	v_mul_f32_e32 v8, v170, v170
	v_mul_f32_e32 v10, v171, v171
	v_pk_add_f32 v[12:13], v[12:13], v[14:15]
	v_pk_add_f32 v[8:9], v[8:9], v[10:11]
	s_nop 0
	v_pk_add_f32 v[8:9], v[12:13], v[8:9]
	s_nop 0
	v_add_f32_e32 v2, v8, v9
	ds_bpermute_b32 v8, v16, v2
	s_waitcnt lgkmcnt(0)
	v_add_f32_e32 v2, v2, v8
	ds_bpermute_b32 v8, v17, v2
	v_lshrrev_b32_e32 v17, 2, v59
	v_or_b32_e32 v41, v40, v17
	s_waitcnt lgkmcnt(0)
	v_add_f32_e32 v2, v2, v8
	v_fmamk_f32 v2, v2, 0x3c800000, v156
	v_cmp_gt_f32_e32 vcc, s75, v2
	v_mul_f32_e32 v8, 0x4b800000, v2
	s_nop 0
	v_cndmask_b32_e32 v2, v2, v8, vcc
	v_rsq_f32_e32 v2, v2
	s_nop 0
	v_mul_f32_e32 v8, 0x45800000, v2
	v_cndmask_b32_e32 v16, v2, v8, vcc
	v_add_u32_e32 v84, s12, v59
	v_readlane_b32 s12, v252, 38
	v_subrev_u32_e32 v84, 63, v84
	v_lshlrev_b32_e32 v8, 3, v46
	v_and_b32_e32 v8, 24, v8
	v_add_u32_e32 v8, s55, v8
	v_mad_u32_u24 v61, v41, s89, v8
	v_lshl_add_u32 v9, v59, 2, s12
	ds_read_b32 v18, v9
	v_lshlrev_b32_e32 v10, 2, v40
	v_add_u32_e32 v19, 0x27600, v10
	v_add_u32_e32 v58, 0x27700, v10
	s_lshl_b32 s13, s0, 8
	s_add_i32 s13, s13, 0x20a00
	v_lshl_add_u32 v74, v46, 4, s13
	v_lshlrev_b32_e32 v56, 11, v84
	v_lshl_add_u32 v56, v44, 1, v56
	ds_read_b128 v[62:65], v19
	ds_read_b128 v[66:69], v58
	ds_read_b64_tr_b16 v[188:189], v61 offset:55296
	ds_read_b128 v[70:73], v74
	ds_read_b128 v[76:79], v19 offset:64
	ds_read_b128 v[184:187], v58 offset:64
	ds_read_b64_tr_b16 v[250:251], v61 offset:57600
	ds_read_b128 v[52:55], v74 offset:1024
	v_readlane_b32 s12, v252, 36
	v_readlane_b32 s13, v252, 37
	s_waitcnt lgkmcnt(4)
	v_pk_mul_f32 v[8:9], v[148:149], v[16:17] op_sel_hi:[1,0]
	v_pk_mul_f32 v[10:11], v[154:155], v[16:17] op_sel_hi:[1,0]
	v_pk_fma_f32 v[8:9], v[62:63], v[8:9], v[66:67]
	v_pk_fma_f32 v[10:11], v[64:65], v[10:11], v[68:69]
	v_lshlrev_b32_e32 v12, 16, v188
	v_and_b32_e32 v13, 0xffff0000, v188
	v_lshlrev_b32_e32 v14, 16, v189
	v_and_b32_e32 v15, 0xffff0000, v189
	v_pk_fma_f32 v[8:9], v[18:19], v[12:13], v[8:9] op_sel_hi:[0,1,1]
	v_pk_fma_f32 v[10:11], v[18:19], v[14:15], v[10:11] op_sel_hi:[0,1,1]
	v_pk_mul_f32 v[8:9], v[70:71], v[8:9]
	v_pk_mul_f32 v[10:11], v[72:73], v[10:11]
	v_cvt_pk_bf16_f32 v8, v8, v9
	v_cvt_pk_bf16_f32 v9, v10, v11
	global_store_dwordx2 v56, v[8:9], s[12:13] offset:1536
	ds_read_b128 v[62:65], v19 offset:128
	ds_read_b128 v[66:69], v58 offset:128
	ds_read_b64_tr_b16 v[188:189], v61 offset:59904
	ds_read_b128 v[70:73], v74 offset:2048
	s_waitcnt lgkmcnt(4)
	v_pk_mul_f32 v[8:9], v[152:153], v[16:17] op_sel_hi:[1,0]
	v_pk_mul_f32 v[10:11], v[150:151], v[16:17] op_sel_hi:[1,0]
	v_pk_fma_f32 v[8:9], v[76:77], v[8:9], v[184:185]
	v_pk_fma_f32 v[10:11], v[78:79], v[10:11], v[186:187]
	v_lshlrev_b32_e32 v12, 16, v250
	v_and_b32_e32 v13, 0xffff0000, v250
	v_lshlrev_b32_e32 v14, 16, v251
	v_and_b32_e32 v15, 0xffff0000, v251
	v_pk_fma_f32 v[8:9], v[18:19], v[12:13], v[8:9] op_sel_hi:[0,1,1]
	v_pk_fma_f32 v[10:11], v[18:19], v[14:15], v[10:11] op_sel_hi:[0,1,1]
	v_pk_mul_f32 v[8:9], v[52:53], v[8:9]
	v_pk_mul_f32 v[10:11], v[54:55], v[10:11]
	v_cvt_pk_bf16_f32 v8, v8, v9
	v_cvt_pk_bf16_f32 v9, v10, v11
	global_store_dwordx2 v56, v[8:9], s[12:13] offset:1568
	ds_read_b128 v[76:79], v19 offset:192
	ds_read_b128 v[184:187], v58 offset:192
	ds_read_b64_tr_b16 v[250:251], v61 offset:62208
	ds_read_b128 v[52:55], v74 offset:3072
	s_waitcnt lgkmcnt(4)
	v_pk_mul_f32 v[8:9], v[172:173], v[16:17] op_sel_hi:[1,0]
	v_pk_mul_f32 v[10:11], v[168:169], v[16:17] op_sel_hi:[1,0]
	v_pk_fma_f32 v[8:9], v[62:63], v[8:9], v[66:67]
	v_pk_fma_f32 v[10:11], v[64:65], v[10:11], v[68:69]
	v_lshlrev_b32_e32 v12, 16, v188
	v_and_b32_e32 v13, 0xffff0000, v188
	v_lshlrev_b32_e32 v14, 16, v189
	v_and_b32_e32 v15, 0xffff0000, v189
	v_pk_fma_f32 v[8:9], v[18:19], v[12:13], v[8:9] op_sel_hi:[0,1,1]
	v_pk_fma_f32 v[10:11], v[18:19], v[14:15], v[10:11] op_sel_hi:[0,1,1]
	v_pk_mul_f32 v[8:9], v[70:71], v[8:9]
	v_pk_mul_f32 v[10:11], v[72:73], v[10:11]
	v_cvt_pk_bf16_f32 v8, v8, v9
	v_cvt_pk_bf16_f32 v9, v10, v11
	global_store_dwordx2 v56, v[8:9], s[12:13] offset:1600
	s_waitcnt lgkmcnt(0)
	v_pk_mul_f32 v[8:9], v[174:175], v[16:17] op_sel_hi:[1,0]
	v_pk_mul_f32 v[10:11], v[170:171], v[16:17] op_sel_hi:[1,0]
	v_pk_fma_f32 v[8:9], v[76:77], v[8:9], v[184:185]
	v_pk_fma_f32 v[10:11], v[78:79], v[10:11], v[186:187]
	v_lshlrev_b32_e32 v12, 16, v250
	v_and_b32_e32 v13, 0xffff0000, v250
	v_lshlrev_b32_e32 v14, 16, v251
	v_and_b32_e32 v15, 0xffff0000, v251
	v_pk_fma_f32 v[8:9], v[18:19], v[12:13], v[8:9] op_sel_hi:[0,1,1]
	v_pk_fma_f32 v[10:11], v[18:19], v[14:15], v[10:11] op_sel_hi:[0,1,1]
	v_pk_mul_f32 v[8:9], v[52:53], v[8:9]
	v_pk_mul_f32 v[10:11], v[54:55], v[10:11]
	v_cvt_pk_bf16_f32 v8, v8, v9
	v_cvt_pk_bf16_f32 v9, v10, v11
	global_store_dwordx2 v56, v[8:9], s[12:13] offset:1632
	s_mov_b64 s[12:13], 0
